# v35 + phase-0 weight-convert tiles: 3 cache-warming loads issued with the first row-group load so the 4 serialized cold round trips per tile become 1 cold + 3 warm
# speedup vs baseline: 1.0063x; 1.0063x over previous
.LBB0_441:
	s_cmpk_gt_i32 s11, 0x2ff
	s_mov_b64 s[12:13], -1
	s_cbranch_scc0 .LBB0_479
	s_cmpk_gt_u32 s11, 0x3ff
	s_cbranch_scc0 .LBB0_476
	s_cmpk_gt_u32 s11, 0x4ff
	s_cbranch_scc0 .LBB0_465
	s_add_i32 s0, s11, 0xfffffb00
	s_cmp_ge_i32 s0, s1
	s_cbranch_scc0 .LBB0_462
	s_add_i32 s16, s47, s11
	s_cmpk_gt_i32 s16, 0xff
	s_cbranch_scc0 .LBB0_459
	s_cmpk_gt_u32 s16, 0x67f
	s_cbranch_scc0 .LBB0_448
	s_load_dwordx2 s[12:13], s[58:59], 0xb0
	v_mov_b32_e32 v8, v243
	s_waitcnt lgkmcnt(0)
	v_ashrrev_i32_e32 v9, 4, v8
	s_add_u32 s14, s12, s19
	s_addc_u32 s13, s13, s18
	s_add_i32 s12, s44, s45
	s_and_b32 s17, s12, 0x7fffffc0
	s_and_b32 s12, s42, 0x3c0
	s_lshl_b32 s15, s12, 2
	s_add_u32 s14, s14, s15
	v_lshlrev_b32_e32 v0, 4, v8
	v_add_u32_e32 v2, s17, v9
	s_addc_u32 s15, s13, 0
	v_and_b32_e32 v0, 0xf0, v0
	v_ashrrev_i32_e32 v3, 31, v2
	v_lshl_add_u64 v[6:7], s[14:15], 0, v[0:1]
	v_lshlrev_b64 v[2:3], 12, v[2:3]
	v_lshl_add_u64 v[2:3], v[6:7], 0, v[2:3]
	v_mov_b32_e32 v70, 0x10000
	v_mov_b32_e32 v71, 0
	v_lshl_add_u64 v[72:73], v[2:3], 0, v[70:71]
	v_lshl_add_u64 v[74:75], v[72:73], 0, v[70:71]
	v_lshl_add_u64 v[76:77], v[74:75], 0, v[70:71]
	s_barrier
	global_load_dwordx4 v[2:5], v[2:3], off
	global_load_dwordx4 v[80:83], v[72:73], off
	global_load_dwordx4 v[80:83], v[74:75], off
	global_load_dwordx4 v[80:83], v[76:77], off
	v_mul_lo_u32 v9, v9, s77
	v_add3_u32 v9, s78, v9, v0
	v_add_u32_e32 v10, 0x100, v8
	s_lshl_b32 s13, s17, 1
	s_add_u32 s14, s20, s13
	s_addc_u32 s15, s21, 0
	s_movk_i32 s13, 0x1600
	s_waitcnt vmcnt(0)
	ds_write2_b32 v9, v2, v3 offset1:1
	ds_write2_b32 v9, v4, v5 offset0:2 offset1:3
	v_ashrrev_i32_e32 v9, 4, v10
	v_add_u32_e32 v2, s17, v9
	v_ashrrev_i32_e32 v3, 31, v2
	v_lshlrev_b64 v[2:3], 12, v[2:3]
	v_lshl_add_u64 v[2:3], v[6:7], 0, v[2:3]
	global_load_dwordx4 v[2:5], v[2:3], off
	v_mul_lo_u32 v9, v9, s77
	v_add3_u32 v9, s78, v9, v0
	s_waitcnt vmcnt(0)
	ds_write2_b32 v9, v2, v3 offset1:1
	ds_write2_b32 v9, v4, v5 offset0:2 offset1:3
	v_add_u32_e32 v2, 0x200, v8
	v_ashrrev_i32_e32 v9, 4, v2
	v_add_u32_e32 v2, s17, v9
	v_ashrrev_i32_e32 v3, 31, v2
	v_lshlrev_b64 v[2:3], 12, v[2:3]
	v_lshl_add_u64 v[2:3], v[6:7], 0, v[2:3]
	global_load_dwordx4 v[2:5], v[2:3], off
	v_mul_lo_u32 v9, v9, s77
	v_add3_u32 v9, s78, v9, v0
	s_waitcnt vmcnt(0)
	ds_write2_b32 v9, v2, v3 offset1:1
	ds_write2_b32 v9, v4, v5 offset0:2 offset1:3
	v_add_u32_e32 v2, 0x300, v8
	v_ashrrev_i32_e32 v9, 4, v2
	v_add_u32_e32 v2, s17, v9
	v_ashrrev_i32_e32 v3, 31, v2
	v_lshlrev_b64 v[2:3], 12, v[2:3]
	v_lshl_add_u64 v[2:3], v[6:7], 0, v[2:3]
	global_load_dwordx4 v[2:5], v[2:3], off
	v_mul_lo_u32 v6, v9, s77
	v_add3_u32 v0, s78, v6, v0
	s_waitcnt vmcnt(0)
	ds_write2_b32 v0, v2, v3 offset1:1
	ds_write2_b32 v0, v4, v5 offset0:2 offset1:3
	v_lshlrev_b32_e32 v0, 3, v8
	v_and_b32_e32 v0, 56, v0
	v_mul_u32_u24_e32 v4, 0x41, v0
	v_lshlrev_b32_e32 v0, 1, v0
	v_lshl_add_u64 v[2:3], s[14:15], 0, v[0:1]
	v_ashrrev_i32_e32 v0, 3, v8
	v_lshlrev_b32_e32 v5, 2, v0
	v_lshlrev_b32_e32 v11, 2, v4
	v_add3_u32 v8, s78, v5, v11
	s_waitcnt lgkmcnt(0)
	s_barrier
	ds_read2_b32 v[4:5], v8 offset1:65
	ds_read2_b32 v[6:7], v8 offset0:130 offset1:195
	v_add_u32_e32 v8, 0x400, v8
	v_add_u32_e32 v0, s12, v0
	s_waitcnt lgkmcnt(1)
	v_cvt_pk_bf16_f32 v4, v4, v5
	s_waitcnt lgkmcnt(0)
	v_cvt_pk_bf16_f32 v5, v6, v7
	ds_read2_b32 v[6:7], v8 offset0:4 offset1:69
	ds_read2_b32 v[8:9], v8 offset0:134 offset1:199
	s_waitcnt lgkmcnt(1)
	v_cvt_pk_bf16_f32 v6, v6, v7
	s_waitcnt lgkmcnt(0)
	v_cvt_pk_bf16_f32 v7, v8, v9
	v_mad_i64_i32 v[8:9], s[14:15], v0, s13, v[2:3]
	v_ashrrev_i32_e32 v0, 3, v10
	global_store_dwordx4 v[8:9], v[4:7], off
	s_nop 1
	v_lshlrev_b32_e32 v4, 2, v0
	v_add3_u32 v8, s78, v4, v11
	ds_read2_b32 v[4:5], v8 offset1:65
	ds_read2_b32 v[6:7], v8 offset0:130 offset1:195
	v_add_u32_e32 v8, 0x400, v8
	v_add_u32_e32 v0, s12, v0
	v_mad_i64_i32 v[2:3], s[12:13], v0, s13, v[2:3]
	s_waitcnt lgkmcnt(1)
	v_cvt_pk_bf16_f32 v4, v4, v5
	s_waitcnt lgkmcnt(0)
	v_cvt_pk_bf16_f32 v5, v6, v7
	ds_read2_b32 v[6:7], v8 offset0:4 offset1:69
	ds_read2_b32 v[8:9], v8 offset0:134 offset1:199
	s_mov_b64 s[12:13], 0
	s_waitcnt lgkmcnt(1)
	v_cvt_pk_bf16_f32 v6, v6, v7
	s_waitcnt lgkmcnt(0)
	v_cvt_pk_bf16_f32 v7, v8, v9
	global_store_dwordx4 v[2:3], v[4:7], off
.LBB0_448:
	s_andn2_b64 vcc, exec, s[12:13]
	s_cbranch_vccnz .LBB0_458
	s_load_dwordx2 s[12:13], s[58:59], 0xa0
	s_load_dwordx2 s[38:39], s[58:59], 0x28
	v_mov_b32_e32 v10, v243
	s_waitcnt lgkmcnt(0)
	s_add_u32 s14, s12, s23
	s_addc_u32 s15, s13, s22
	s_lshl_b64 s[12:13], s[4:5], 2
	s_add_u32 s12, s38, s12
	s_addc_u32 s13, s39, s13
	s_add_i32 s52, s16, 0xff00
	s_and_b32 s17, s52, 0xffff
	s_mul_i32 s17, s17, 0xba2f
	s_lshr_b32 s53, s17, 22
	s_mulk_i32 s53, 0x58
	s_sub_i32 s52, s52, s53
	s_lshr_b32 s17, s17, 16
	s_lshl_b32 s53, s52, 8
	s_and_b32 s17, s17, 0xffc0
	s_and_b32 s53, s53, 0x3ff00
	v_lshlrev_b32_e32 v0, 2, v10
	s_add_u32 s14, s14, s53
	v_and_b32_e32 v0, 60, v0
	s_addc_u32 s15, s15, 0
	v_lshlrev_b32_e32 v0, 2, v0
	v_ashrrev_i32_e32 v11, 4, v10
	v_lshl_add_u64 v[6:7], s[14:15], 0, v[0:1]
	v_add_u32_e32 v8, s17, v11
	v_mad_i64_i32 v[2:3], s[14:15], v8, s74, v[6:7]
	v_mov_b32_e32 v70, s74
	v_lshlrev_b32_e32 v70, 4, v70
	v_mov_b32_e32 v71, 0
	v_lshl_add_u64 v[72:73], v[2:3], 0, v[70:71]
	v_lshl_add_u64 v[74:75], v[72:73], 0, v[70:71]
	v_lshl_add_u64 v[76:77], v[74:75], 0, v[70:71]
	s_barrier
	global_load_dwordx4 v[2:5], v[2:3], off
	global_load_dwordx4 v[80:83], v[72:73], off
	global_load_dwordx4 v[80:83], v[74:75], off
	global_load_dwordx4 v[80:83], v[76:77], off
	s_cmp_lg_u64 s[38:39], 0
	s_cselect_b64 s[14:15], -1, 0
	s_cmp_eq_u64 s[38:39], 0
	s_cbranch_scc1 .LBB0_451
	v_ashrrev_i32_e32 v9, 31, v8
	v_lshl_add_u64 v[8:9], v[8:9], 2, s[12:13]
	global_load_dword v8, v[8:9], off
	s_waitcnt vmcnt(0)
	v_pk_mul_f32 v[4:5], v[4:5], v[8:9] op_sel_hi:[1,0]
	v_pk_mul_f32 v[2:3], v[2:3], v[8:9] op_sel_hi:[1,0]

.LBB0_459:
	s_andn2_b64 vcc, exec, s[12:13]
	s_cbranch_vccnz .LBB0_461
	s_load_dwordx2 s[12:13], s[58:59], 0x98
	v_mov_b32_e32 v8, v243
	s_waitcnt lgkmcnt(0)
	v_ashrrev_i32_e32 v9, 4, v8
	s_add_u32 s15, s12, s6
	s_sext_i32_i16 s12, s16
	s_addc_u32 s38, s13, s7
	s_bfe_u32 s12, s12, 0x4001b
	s_add_i32 s12, s16, s12
	s_sext_i32_i16 s13, s12
	s_and_b32 s12, s12, 0xfff0
	s_sub_i32 s12, s16, s12
	s_sext_i32_i16 s12, s12
	s_lshl_b32 s13, s13, 2
	s_lshl_b32 s12, s12, 6
	s_and_b32 s14, s13, 0xffffffc0
	s_ashr_i32 s13, s12, 31
	s_lshl_b64 s[16:17], s[12:13], 2
	s_add_u32 s16, s15, s16
	v_lshlrev_b32_e32 v0, 4, v8
	v_add_u32_e32 v2, s14, v9
	s_addc_u32 s17, s38, s17
	v_and_b32_e32 v0, 0xf0, v0
	v_ashrrev_i32_e32 v3, 31, v2
	v_lshl_add_u64 v[6:7], s[16:17], 0, v[0:1]
	v_lshlrev_b64 v[2:3], 12, v[2:3]
	v_lshl_add_u64 v[2:3], v[6:7], 0, v[2:3]
	v_mov_b32_e32 v70, 0x10000
	v_mov_b32_e32 v71, 0
	v_lshl_add_u64 v[72:73], v[2:3], 0, v[70:71]
	v_lshl_add_u64 v[74:75], v[72:73], 0, v[70:71]
	v_lshl_add_u64 v[76:77], v[74:75], 0, v[70:71]
	s_barrier
	global_load_dwordx4 v[2:5], v[2:3], off
	global_load_dwordx4 v[80:83], v[72:73], off
	global_load_dwordx4 v[80:83], v[74:75], off
	global_load_dwordx4 v[80:83], v[76:77], off
	v_mul_lo_u32 v9, v9, s77
	v_add3_u32 v9, s78, v9, v0
	v_add_u32_e32 v10, 0x100, v8
	s_ashr_i32 s15, s14, 31
	s_waitcnt vmcnt(0)
	ds_write2_b32 v9, v2, v3 offset1:1
	ds_write2_b32 v9, v4, v5 offset0:2 offset1:3
	v_ashrrev_i32_e32 v9, 4, v10
	v_add_u32_e32 v2, s14, v9
	v_ashrrev_i32_e32 v3, 31, v2
	v_lshlrev_b64 v[2:3], 12, v[2:3]
	v_lshl_add_u64 v[2:3], v[6:7], 0, v[2:3]
	global_load_dwordx4 v[2:5], v[2:3], off
	v_mul_lo_u32 v9, v9, s77
	v_add3_u32 v9, s78, v9, v0
	s_waitcnt vmcnt(0)
	ds_write2_b32 v9, v2, v3 offset1:1
	ds_write2_b32 v9, v4, v5 offset0:2 offset1:3
	v_add_u32_e32 v2, 0x200, v8
	v_ashrrev_i32_e32 v9, 4, v2
	v_add_u32_e32 v2, s14, v9
	v_ashrrev_i32_e32 v3, 31, v2
	v_lshlrev_b64 v[2:3], 12, v[2:3]
	v_lshl_add_u64 v[2:3], v[6:7], 0, v[2:3]
	global_load_dwordx4 v[2:5], v[2:3], off
	v_mul_lo_u32 v9, v9, s77
	v_add3_u32 v9, s78, v9, v0
	s_waitcnt vmcnt(0)
	ds_write2_b32 v9, v2, v3 offset1:1
	ds_write2_b32 v9, v4, v5 offset0:2 offset1:3
	v_add_u32_e32 v2, 0x300, v8
	v_ashrrev_i32_e32 v9, 4, v2
	v_add_u32_e32 v2, s14, v9
	v_ashrrev_i32_e32 v3, 31, v2
	v_lshlrev_b64 v[2:3], 12, v[2:3]
	v_lshl_add_u64 v[2:3], v[6:7], 0, v[2:3]
	global_load_dwordx4 v[2:5], v[2:3], off
	v_mul_lo_u32 v6, v9, s77
	v_add3_u32 v0, s78, v6, v0
	s_lshl_b64 s[14:15], s[14:15], 1
	s_add_u32 s14, s26, s14
	s_addc_u32 s15, s27, s15
	s_waitcnt vmcnt(0)
	ds_write2_b32 v0, v2, v3 offset1:1
	ds_write2_b32 v0, v4, v5 offset0:2 offset1:3
	v_lshlrev_b32_e32 v0, 3, v8
	v_and_b32_e32 v0, 56, v0
	v_mul_u32_u24_e32 v4, 0x41, v0
	v_lshlrev_b32_e32 v0, 1, v0
	v_lshl_add_u64 v[2:3], s[14:15], 0, v[0:1]
	v_ashrrev_i32_e32 v0, 3, v8
	v_lshlrev_b32_e32 v5, 2, v0
	v_lshlrev_b32_e32 v11, 2, v4
	v_add3_u32 v8, s78, v5, v11
	s_waitcnt lgkmcnt(0)
	s_barrier
	ds_read2_b32 v[4:5], v8 offset1:65
	ds_read2_b32 v[6:7], v8 offset0:130 offset1:195
	v_add_u32_e32 v8, 0x400, v8
	s_waitcnt lgkmcnt(1)
	v_cvt_pk_bf16_f32 v4, v4, v5
	s_waitcnt lgkmcnt(0)
	v_cvt_pk_bf16_f32 v5, v6, v7
	ds_read2_b32 v[6:7], v8 offset0:4 offset1:69
	ds_read2_b32 v[8:9], v8 offset0:134 offset1:199
	s_waitcnt lgkmcnt(1)
	v_cvt_pk_bf16_f32 v6, v6, v7
	s_waitcnt lgkmcnt(0)
	v_cvt_pk_bf16_f32 v7, v8, v9
	v_add_u32_e32 v8, s12, v0
	v_ashrrev_i32_e32 v9, 31, v8
	v_lshlrev_b64 v[8:9], 11, v[8:9]
	v_lshl_add_u64 v[8:9], v[2:3], 0, v[8:9]
	v_ashrrev_i32_e32 v0, 3, v10
	global_store_dwordx4 v[8:9], v[4:7], off
	s_nop 1
	v_lshlrev_b32_e32 v4, 2, v0
	v_add3_u32 v8, s78, v4, v11
	ds_read2_b32 v[4:5], v8 offset1:65
	ds_read2_b32 v[6:7], v8 offset0:130 offset1:195
	v_add_u32_e32 v8, 0x400, v8
	s_waitcnt lgkmcnt(1)
	v_cvt_pk_bf16_f32 v4, v4, v5
	s_waitcnt lgkmcnt(0)
	v_cvt_pk_bf16_f32 v5, v6, v7
	ds_read2_b32 v[6:7], v8 offset0:4 offset1:69
	ds_read2_b32 v[8:9], v8 offset0:134 offset1:199
	s_waitcnt lgkmcnt(1)
	v_cvt_pk_bf16_f32 v6, v6, v7
	s_waitcnt lgkmcnt(0)
	v_cvt_pk_bf16_f32 v7, v8, v9
	v_add_u32_e32 v8, s12, v0
	v_ashrrev_i32_e32 v9, 31, v8
	v_lshlrev_b64 v[8:9], 11, v[8:9]
	v_lshl_add_u64 v[2:3], v[2:3], 0, v[8:9]
	global_store_dwordx4 v[2:3], v[4:7], off

.LBB0_462:
	s_andn2_b64 vcc, exec, s[12:13]
	s_cbranch_vccnz .LBB0_464
	s_load_dwordx2 s[12:13], s[58:59], 0x80
	s_lshr_b32 s80, s0, 9
	s_lshl_b64 s[14:15], s[80:81], 23
	v_mov_b32_e32 v8, v243
	s_waitcnt lgkmcnt(0)
	s_add_u32 s14, s12, s14
	s_addc_u32 s15, s13, s15
	s_lshl_b64 s[12:13], s[80:81], 22
	s_add_u32 s16, s28, s12
	s_addc_u32 s17, s29, s13
	s_and_b32 s0, s42, 0x7c0
	s_and_b32 s38, s48, 0x3c0
	s_lshl_b32 s12, s0, 2
	v_ashrrev_i32_e32 v9, 4, v8
	s_add_u32 s12, s14, s12
	v_lshlrev_b32_e32 v0, 4, v8
	v_add_u32_e32 v2, s38, v9
	s_addc_u32 s13, s15, 0
	v_and_b32_e32 v0, 0xf0, v0
	v_ashrrev_i32_e32 v3, 31, v2
	v_lshl_add_u64 v[6:7], s[12:13], 0, v[0:1]
	v_lshlrev_b64 v[2:3], 13, v[2:3]
	v_lshl_add_u64 v[2:3], v[6:7], 0, v[2:3]
	v_mov_b32_e32 v70, 0x20000
	v_mov_b32_e32 v71, 0
	v_lshl_add_u64 v[72:73], v[2:3], 0, v[70:71]
	v_lshl_add_u64 v[74:75], v[72:73], 0, v[70:71]
	v_lshl_add_u64 v[76:77], v[74:75], 0, v[70:71]
	s_barrier
	global_load_dwordx4 v[2:5], v[2:3], off
	global_load_dwordx4 v[80:83], v[72:73], off
	global_load_dwordx4 v[80:83], v[74:75], off
	global_load_dwordx4 v[80:83], v[76:77], off
	v_mul_lo_u32 v9, v9, s77
	v_add3_u32 v9, s78, v9, v0
	v_add_u32_e32 v10, 0x100, v8
	s_lshl_b32 s12, s38, 1
	s_add_u32 s12, s16, s12
	s_addc_u32 s13, s17, 0
	s_waitcnt vmcnt(0)
	ds_write2_b32 v9, v2, v3 offset1:1
	ds_write2_b32 v9, v4, v5 offset0:2 offset1:3
	v_ashrrev_i32_e32 v9, 4, v10
	v_add_u32_e32 v2, s38, v9
	v_ashrrev_i32_e32 v3, 31, v2
	v_lshlrev_b64 v[2:3], 13, v[2:3]
	v_lshl_add_u64 v[2:3], v[6:7], 0, v[2:3]
	global_load_dwordx4 v[2:5], v[2:3], off
	v_mul_lo_u32 v9, v9, s77
	v_add3_u32 v9, s78, v9, v0
	s_waitcnt vmcnt(0)
	ds_write2_b32 v9, v2, v3 offset1:1
	ds_write2_b32 v9, v4, v5 offset0:2 offset1:3
	v_add_u32_e32 v2, 0x200, v8
	v_ashrrev_i32_e32 v9, 4, v2
	v_add_u32_e32 v2, s38, v9
	v_ashrrev_i32_e32 v3, 31, v2
	v_lshlrev_b64 v[2:3], 13, v[2:3]
	v_lshl_add_u64 v[2:3], v[6:7], 0, v[2:3]
	global_load_dwordx4 v[2:5], v[2:3], off
	v_mul_lo_u32 v9, v9, s77
	v_add3_u32 v9, s78, v9, v0
	s_waitcnt vmcnt(0)
	ds_write2_b32 v9, v2, v3 offset1:1
	ds_write2_b32 v9, v4, v5 offset0:2 offset1:3
	v_add_u32_e32 v2, 0x300, v8
	v_ashrrev_i32_e32 v9, 4, v2
	v_add_u32_e32 v2, s38, v9
	v_ashrrev_i32_e32 v3, 31, v2
	v_lshlrev_b64 v[2:3], 13, v[2:3]
	v_lshl_add_u64 v[2:3], v[6:7], 0, v[2:3]
	global_load_dwordx4 v[2:5], v[2:3], off
	v_mul_lo_u32 v6, v9, s77
	v_add3_u32 v0, s78, v6, v0
	s_waitcnt vmcnt(0)
	ds_write2_b32 v0, v2, v3 offset1:1
	ds_write2_b32 v0, v4, v5 offset0:2 offset1:3
	v_lshlrev_b32_e32 v0, 3, v8
	v_and_b32_e32 v0, 56, v0
	v_mul_u32_u24_e32 v4, 0x41, v0
	v_lshlrev_b32_e32 v0, 1, v0
	v_lshl_add_u64 v[2:3], s[12:13], 0, v[0:1]
	v_ashrrev_i32_e32 v0, 3, v8
	v_lshlrev_b32_e32 v5, 2, v0
	v_lshlrev_b32_e32 v11, 2, v4
	v_add3_u32 v8, s78, v5, v11
	s_waitcnt lgkmcnt(0)
	s_barrier
	ds_read2_b32 v[4:5], v8 offset1:65
	ds_read2_b32 v[6:7], v8 offset0:130 offset1:195
	v_add_u32_e32 v8, 0x400, v8
	s_waitcnt lgkmcnt(1)
	v_cvt_pk_bf16_f32 v4, v4, v5
	s_waitcnt lgkmcnt(0)
	v_cvt_pk_bf16_f32 v5, v6, v7
	ds_read2_b32 v[6:7], v8 offset0:4 offset1:69
	ds_read2_b32 v[8:9], v8 offset0:134 offset1:199
	s_waitcnt lgkmcnt(1)
	v_cvt_pk_bf16_f32 v6, v6, v7
	s_waitcnt lgkmcnt(0)
	v_cvt_pk_bf16_f32 v7, v8, v9
	v_add_u32_e32 v8, s0, v0
	v_ashrrev_i32_e32 v9, 31, v8
	v_lshlrev_b64 v[8:9], 11, v[8:9]
	v_lshl_add_u64 v[8:9], v[2:3], 0, v[8:9]
	v_ashrrev_i32_e32 v0, 3, v10
	global_store_dwordx4 v[8:9], v[4:7], off
	s_nop 1
	v_lshlrev_b32_e32 v4, 2, v0
	v_add3_u32 v8, s78, v4, v11
	ds_read2_b32 v[4:5], v8 offset1:65
	ds_read2_b32 v[6:7], v8 offset0:130 offset1:195
	v_add_u32_e32 v8, 0x400, v8
	s_waitcnt lgkmcnt(1)
	v_cvt_pk_bf16_f32 v4, v4, v5
	s_waitcnt lgkmcnt(0)
	v_cvt_pk_bf16_f32 v5, v6, v7
	ds_read2_b32 v[6:7], v8 offset0:4 offset1:69
	ds_read2_b32 v[8:9], v8 offset0:134 offset1:199
	s_waitcnt lgkmcnt(1)
	v_cvt_pk_bf16_f32 v6, v6, v7
	s_waitcnt lgkmcnt(0)
	v_cvt_pk_bf16_f32 v7, v8, v9
	v_add_u32_e32 v8, s0, v0
	v_ashrrev_i32_e32 v9, 31, v8
	v_lshlrev_b64 v[8:9], 11, v[8:9]
	v_lshl_add_u64 v[2:3], v[2:3], 0, v[8:9]
	global_store_dwordx4 v[2:3], v[4:7], off

.LBB0_465:
	s_andn2_b64 vcc, exec, s[12:13]
	s_cbranch_vccnz .LBB0_475
	s_load_dwordx2 s[12:13], s[58:59], 0x78
	s_load_dwordx2 s[38:39], s[58:59], 0x18
	v_mov_b32_e32 v10, v243
	s_waitcnt lgkmcnt(0)
	s_add_u32 s14, s12, s6
	s_addc_u32 s15, s13, s7
	s_lshl_b64 s[12:13], s[4:5], 2
	s_add_u32 s12, s38, s12
	s_addc_u32 s13, s39, s13
	s_and_b32 s0, s42, 0x3c0
	s_and_b32 s16, s45, 0x3c0
	s_lshl_b32 s17, s0, 2
	v_lshlrev_b32_e32 v0, 2, v10
	v_ashrrev_i32_e32 v11, 4, v10
	s_add_u32 s14, s14, s17
	v_and_b32_e32 v0, 60, v0
	v_add_u32_e32 v8, s16, v11
	s_addc_u32 s15, s15, 0
	v_lshlrev_b32_e32 v0, 2, v0
	v_ashrrev_i32_e32 v9, 31, v8
	v_lshl_add_u64 v[6:7], s[14:15], 0, v[0:1]
	v_lshlrev_b64 v[2:3], 12, v[8:9]
	v_lshl_add_u64 v[2:3], v[6:7], 0, v[2:3]
	v_mov_b32_e32 v70, 0x10000
	v_mov_b32_e32 v71, 0
	v_lshl_add_u64 v[72:73], v[2:3], 0, v[70:71]
	v_lshl_add_u64 v[74:75], v[72:73], 0, v[70:71]
	v_lshl_add_u64 v[76:77], v[74:75], 0, v[70:71]
	s_barrier
	global_load_dwordx4 v[2:5], v[2:3], off
	global_load_dwordx4 v[80:83], v[72:73], off
	global_load_dwordx4 v[80:83], v[74:75], off
	global_load_dwordx4 v[80:83], v[76:77], off
	s_cmp_lg_u64 s[38:39], 0
	s_cselect_b64 s[14:15], -1, 0
	s_cmp_eq_u64 s[38:39], 0
	s_cbranch_scc1 .LBB0_468
	v_lshl_add_u64 v[8:9], v[8:9], 2, s[12:13]
	global_load_dword v8, v[8:9], off
	s_waitcnt vmcnt(0)
	v_pk_mul_f32 v[4:5], v[4:5], v[8:9] op_sel_hi:[1,0]
	v_pk_mul_f32 v[2:3], v[2:3], v[8:9] op_sel_hi:[1,0]

.LBB0_476:
	s_andn2_b64 vcc, exec, s[12:13]
	s_cbranch_vccnz .LBB0_478
	s_add_u32 s12, s58, s40
	s_addc_u32 s13, s59, 0
	s_load_dwordx2 s[12:13], s[12:13], 0x0
	v_mov_b32_e32 v8, v243
	s_waitcnt lgkmcnt(0)
	v_ashrrev_i32_e32 v9, 4, v8
	s_add_u32 s12, s12, s8
	s_addc_u32 s13, s13, s9
	s_and_b32 s0, s42, 0x3c0
	s_and_b32 s14, s45, 0x3c0
	s_lshl_b32 s15, s0, 2
	s_add_u32 s12, s12, s15
	v_lshlrev_b32_e32 v0, 4, v8
	v_add_u32_e32 v2, s14, v9
	s_addc_u32 s13, s13, 0
	v_and_b32_e32 v0, 0xf0, v0
	v_ashrrev_i32_e32 v3, 31, v2
	v_lshl_add_u64 v[6:7], s[12:13], 0, v[0:1]
	v_lshlrev_b64 v[2:3], 12, v[2:3]
	v_lshl_add_u64 v[2:3], v[6:7], 0, v[2:3]
	v_mov_b32_e32 v70, 0x10000
	v_mov_b32_e32 v71, 0
	v_lshl_add_u64 v[72:73], v[2:3], 0, v[70:71]
	v_lshl_add_u64 v[74:75], v[72:73], 0, v[70:71]
	v_lshl_add_u64 v[76:77], v[74:75], 0, v[70:71]
	s_barrier
	global_load_dwordx4 v[2:5], v[2:3], off
	global_load_dwordx4 v[80:83], v[72:73], off
	global_load_dwordx4 v[80:83], v[74:75], off
	global_load_dwordx4 v[80:83], v[76:77], off
	v_mul_lo_u32 v9, v9, s77
	v_add3_u32 v9, s78, v9, v0
	v_add_u32_e32 v10, 0x100, v8
	s_lshl_b32 s12, s14, 1
	s_add_u32 s12, s34, s12
	s_addc_u32 s13, s35, 0
	s_waitcnt vmcnt(0)
	ds_write2_b32 v9, v2, v3 offset1:1
	ds_write2_b32 v9, v4, v5 offset0:2 offset1:3
	v_ashrrev_i32_e32 v9, 4, v10
	v_add_u32_e32 v2, s14, v9
	v_ashrrev_i32_e32 v3, 31, v2
	v_lshlrev_b64 v[2:3], 12, v[2:3]
	v_lshl_add_u64 v[2:3], v[6:7], 0, v[2:3]
	global_load_dwordx4 v[2:5], v[2:3], off
	v_mul_lo_u32 v9, v9, s77
	v_add3_u32 v9, s78, v9, v0
	s_waitcnt vmcnt(0)
	ds_write2_b32 v9, v2, v3 offset1:1
	ds_write2_b32 v9, v4, v5 offset0:2 offset1:3
	v_add_u32_e32 v2, 0x200, v8
	v_ashrrev_i32_e32 v9, 4, v2
	v_add_u32_e32 v2, s14, v9
	v_ashrrev_i32_e32 v3, 31, v2
	v_lshlrev_b64 v[2:3], 12, v[2:3]
	v_lshl_add_u64 v[2:3], v[6:7], 0, v[2:3]
	global_load_dwordx4 v[2:5], v[2:3], off
	v_mul_lo_u32 v9, v9, s77
	v_add3_u32 v9, s78, v9, v0
	s_waitcnt vmcnt(0)
	ds_write2_b32 v9, v2, v3 offset1:1
	ds_write2_b32 v9, v4, v5 offset0:2 offset1:3
	v_add_u32_e32 v2, 0x300, v8
	v_ashrrev_i32_e32 v9, 4, v2
	v_add_u32_e32 v2, s14, v9
	v_ashrrev_i32_e32 v3, 31, v2
	v_lshlrev_b64 v[2:3], 12, v[2:3]
	v_lshl_add_u64 v[2:3], v[6:7], 0, v[2:3]
	global_load_dwordx4 v[2:5], v[2:3], off
	v_mul_lo_u32 v6, v9, s77
	v_add3_u32 v0, s78, v6, v0
	s_waitcnt vmcnt(0)
	ds_write2_b32 v0, v2, v3 offset1:1
	ds_write2_b32 v0, v4, v5 offset0:2 offset1:3
	v_lshlrev_b32_e32 v0, 3, v8
	v_and_b32_e32 v0, 56, v0
	v_mul_u32_u24_e32 v4, 0x41, v0
	v_lshlrev_b32_e32 v0, 1, v0
	v_lshl_add_u64 v[2:3], s[12:13], 0, v[0:1]
	v_ashrrev_i32_e32 v0, 3, v8
	v_lshlrev_b32_e32 v5, 2, v0
	v_lshlrev_b32_e32 v11, 2, v4
	v_add3_u32 v8, s78, v5, v11
	s_waitcnt lgkmcnt(0)
	s_barrier
	ds_read2_b32 v[4:5], v8 offset1:65
	ds_read2_b32 v[6:7], v8 offset0:130 offset1:195
	v_add_u32_e32 v8, 0x400, v8
	s_waitcnt lgkmcnt(1)
	v_cvt_pk_bf16_f32 v4, v4, v5
	s_waitcnt lgkmcnt(0)
	v_cvt_pk_bf16_f32 v5, v6, v7
	ds_read2_b32 v[6:7], v8 offset0:4 offset1:69
	ds_read2_b32 v[8:9], v8 offset0:134 offset1:199
	s_waitcnt lgkmcnt(1)
	v_cvt_pk_bf16_f32 v6, v6, v7
	s_waitcnt lgkmcnt(0)
	v_cvt_pk_bf16_f32 v7, v8, v9
	v_add_u32_e32 v8, s0, v0
	v_ashrrev_i32_e32 v9, 31, v8
	v_lshlrev_b64 v[8:9], 11, v[8:9]
	v_lshl_add_u64 v[8:9], v[2:3], 0, v[8:9]
	v_ashrrev_i32_e32 v0, 3, v10
	global_store_dwordx4 v[8:9], v[4:7], off
	s_nop 1
	v_lshlrev_b32_e32 v4, 2, v0
	v_add3_u32 v8, s78, v4, v11
	ds_read2_b32 v[4:5], v8 offset1:65
	ds_read2_b32 v[6:7], v8 offset0:130 offset1:195
	v_add_u32_e32 v8, 0x400, v8
	s_waitcnt lgkmcnt(1)
	v_cvt_pk_bf16_f32 v4, v4, v5
	s_waitcnt lgkmcnt(0)
	v_cvt_pk_bf16_f32 v5, v6, v7
	ds_read2_b32 v[6:7], v8 offset0:4 offset1:69
	ds_read2_b32 v[8:9], v8 offset0:134 offset1:199
	s_waitcnt lgkmcnt(1)
	v_cvt_pk_bf16_f32 v6, v6, v7
	s_waitcnt lgkmcnt(0)
	v_cvt_pk_bf16_f32 v7, v8, v9
	v_add_u32_e32 v8, s0, v0
	v_ashrrev_i32_e32 v9, 31, v8
	v_lshlrev_b64 v[8:9], 11, v[8:9]
	v_lshl_add_u64 v[2:3], v[2:3], 0, v[8:9]
	global_store_dwordx4 v[2:3], v[4:7], off

.LBB0_479:
	s_andn2_b64 vcc, exec, s[12:13]
	s_cbranch_vccnz .LBB0_440
	s_add_u32 s12, s58, s41
	s_addc_u32 s13, s59, 0
	s_load_dwordx2 s[12:13], s[12:13], 0x0
	s_mul_hi_i32 s0, s11, 0x2aaaaaab
	s_load_dwordx2 s[38:39], s[58:59], 0x10
	v_mov_b32_e32 v10, v243
	s_waitcnt lgkmcnt(0)
	s_add_u32 s52, s12, s37
	s_addc_u32 s53, s13, s36
	s_lshl_b64 s[12:13], s[4:5], 2
	s_add_u32 s14, s38, s12
	s_addc_u32 s15, s39, s13
	s_lshr_b32 s12, s0, 31
	s_ashr_i32 s0, s0, 3
	s_add_i32 s0, s0, s12
	s_mul_i32 s13, s0, 0xfffff400
	s_add_i32 s16, s42, s13
	s_ashr_i32 s17, s16, 31
	s_lshl_b32 s12, s0, 6
	s_lshl_b64 s[16:17], s[16:17], 2
	v_lshlrev_b32_e32 v0, 2, v10
	s_add_u32 s16, s52, s16
	v_and_b32_e32 v0, 60, v0
	s_addc_u32 s17, s53, s17
	v_lshlrev_b32_e32 v0, 2, v0
	v_ashrrev_i32_e32 v11, 4, v10
	v_lshl_add_u64 v[6:7], s[16:17], 0, v[0:1]
	v_add_u32_e32 v8, s12, v11
	v_mad_i64_i32 v[2:3], s[16:17], v8, s76, v[6:7]
	v_mov_b32_e32 v70, s76
	v_lshlrev_b32_e32 v70, 4, v70
	v_mov_b32_e32 v71, 0
	v_lshl_add_u64 v[72:73], v[2:3], 0, v[70:71]
	v_lshl_add_u64 v[74:75], v[72:73], 0, v[70:71]
	v_lshl_add_u64 v[76:77], v[74:75], 0, v[70:71]
	s_barrier
	global_load_dwordx4 v[2:5], v[2:3], off
	global_load_dwordx4 v[80:83], v[72:73], off
	global_load_dwordx4 v[80:83], v[74:75], off
	global_load_dwordx4 v[80:83], v[76:77], off
	s_cmp_lg_u64 s[38:39], 0
	s_cselect_b64 s[16:17], -1, 0
	s_cmp_eq_u64 s[38:39], 0
	s_cbranch_scc1 .LBB0_482
	v_ashrrev_i32_e32 v9, 31, v8
	v_lshl_add_u64 v[8:9], v[8:9], 2, s[14:15]
	global_load_dword v8, v[8:9], off
	s_waitcnt vmcnt(0)
	v_pk_mul_f32 v[4:5], v[4:5], v[8:9] op_sel_hi:[1,0]
	v_pk_mul_f32 v[2:3], v[2:3], v[8:9] op_sel_hi:[1,0]
